# P0 Pb f32->bf16 conversion loop: 9 independent loads in flight per thread with scalar bases instead of 8.5 serial iterations
# speedup vs baseline: 1.0047x; 1.0047x over previous
; #define GAS __attribute__((address_space(1)))
; __device__ __forceinline__ unsigned pk2(float lo, float hi) { return pg8::cvt_pk_bf16(lo, hi); }
; __device__ __forceinline__ void p0_prologue(ArgP A, LAS unsigned char* lds, int tid, int lane, int wave, int bid, int G) {
;     ...
;     for (int i = gt; i < 2 * MT * 64; i += NGT) { const int layer = i / (MT * 64), rem = i % (MT * 64), m = rem >> 6, c4 = rem & 63;
;         const GAS float* src = (m < MP) ? A->in[6] + ((size_t)layer * MP + m) * PLED : A->in[7] + ((size_t)layer * MS + (m - MP)) * PLED;
;         const f32x4 v = __builtin_nontemporal_load(&((const GAS f32x4*)src)[c4]); u32x2 w; w.x = pk2(v.x, v.y); w.y = pk2(v.z, v.w); ((GAS u32x2*)(A->ws + WS_PB))[i] = w; }
;     for (int m = gw; m < MT; m += NGW) row_rms_bf16<true>(xrow(A, 0, m), A->in[8], (GAS bf16*)(A->ws + WS_XN) + (size_t)m * DM, lane);
.LBB0_36:
	s_or_b64 exec, exec, s[2:3]
	v_readlane_b32 s72, v251, 5
	v_readlane_b32 s74, v251, 7
	v_readlane_b32 s73, v251, 6
	v_readlane_b32 s75, v251, 8
	s_load_dwordx2 s[4:5], s[16:17], 0x30
	s_load_dwordx2 s[14:15], s[16:17], 0x38
	s_load_dwordx2 s[18:19], s[16:17], 0x138
	v_lshlrev_b32_e32 v1, 4, v10
	v_lshlrev_b32_e32 v2, 3, v10
	s_lshr_b32 s13, s70, 6
	s_waitcnt lgkmcnt(0)
	s_cmp_lt_u32 s13, 2
	s_cbranch_scc0 .Lpb_no8
	s_add_u32 s2, s4, 0xf80000
	s_addc_u32 s3, s5, 0
	s_cmp_eq_u32 s13, 0
	s_cselect_b32 s2, s2, s14
	s_cselect_b32 s3, s3, s15
	global_load_dwordx4 v[50:53], v1, s[2:3] nt
.Lpb_no8:
	global_load_dwordx4 v[18:21], v1, s[4:5] nt
	s_add_u32 s2, s4, 0x200000
	s_addc_u32 s3, s5, 0
	global_load_dwordx4 v[22:25], v1, s[2:3] nt
	s_add_u32 s2, s4, 0x400000
	s_addc_u32 s3, s5, 0
	global_load_dwordx4 v[26:29], v1, s[2:3] nt
	s_add_u32 s2, s4, 0x600000
	s_addc_u32 s3, s5, 0
	global_load_dwordx4 v[30:33], v1, s[2:3] nt
	s_add_u32 s2, s4, 0x780000
	s_addc_u32 s3, s5, 0
	s_cmp_eq_u32 s13, 0
	s_cselect_b32 s2, s14, s2
	s_cselect_b32 s3, s15, s3
	global_load_dwordx4 v[34:37], v1, s[2:3] nt
	s_add_u32 s2, s4, 0x980000
	s_addc_u32 s3, s5, 0
	global_load_dwordx4 v[38:41], v1, s[2:3] nt
	s_add_u32 s2, s4, 0xb80000
	s_addc_u32 s3, s5, 0
	global_load_dwordx4 v[42:45], v1, s[2:3] nt
	s_add_u32 s2, s4, 0xd80000
	s_addc_u32 s3, s5, 0
	global_load_dwordx4 v[46:49], v1, s[2:3] nt
	s_add_u32 s18, s18, 0xd000000
	s_addc_u32 s19, s19, 0
	s_waitcnt vmcnt(7)
	v_cvt_pk_bf16_f32 v18, v18, v19
	v_cvt_pk_bf16_f32 v19, v20, v21
	global_store_dwordx2 v2, v[18:19], s[18:19]
	s_waitcnt vmcnt(7)
	v_cvt_pk_bf16_f32 v22, v22, v23
	v_cvt_pk_bf16_f32 v23, v24, v25
	s_add_u32 s2, s18, 0x100000
	s_addc_u32 s3, s19, 0
	global_store_dwordx2 v2, v[22:23], s[2:3]
	s_waitcnt vmcnt(7)
	v_cvt_pk_bf16_f32 v26, v26, v27
	v_cvt_pk_bf16_f32 v27, v28, v29
	s_add_u32 s2, s18, 0x200000
	s_addc_u32 s3, s19, 0
	global_store_dwordx2 v2, v[26:27], s[2:3]
	s_waitcnt vmcnt(7)
	v_cvt_pk_bf16_f32 v30, v30, v31
	v_cvt_pk_bf16_f32 v31, v32, v33
	s_add_u32 s2, s18, 0x300000
	s_addc_u32 s3, s19, 0
	global_store_dwordx2 v2, v[30:31], s[2:3]
	s_waitcnt vmcnt(7)
	v_cvt_pk_bf16_f32 v34, v34, v35
	v_cvt_pk_bf16_f32 v35, v36, v37
	s_add_u32 s2, s18, 0x400000
	s_addc_u32 s3, s19, 0
	global_store_dwordx2 v2, v[34:35], s[2:3]
	s_waitcnt vmcnt(7)
	v_cvt_pk_bf16_f32 v38, v38, v39
	v_cvt_pk_bf16_f32 v39, v40, v41
	s_add_u32 s2, s18, 0x500000
	s_addc_u32 s3, s19, 0
	global_store_dwordx2 v2, v[38:39], s[2:3]
	s_waitcnt vmcnt(7)
	v_cvt_pk_bf16_f32 v42, v42, v43
	v_cvt_pk_bf16_f32 v43, v44, v45
	s_add_u32 s2, s18, 0x600000
	s_addc_u32 s3, s19, 0
	global_store_dwordx2 v2, v[42:43], s[2:3]
	s_waitcnt vmcnt(7)
	v_cvt_pk_bf16_f32 v46, v46, v47
	v_cvt_pk_bf16_f32 v47, v48, v49
	s_add_u32 s2, s18, 0x700000
	s_addc_u32 s3, s19, 0
	global_store_dwordx2 v2, v[46:47], s[2:3]
	s_cmp_lt_u32 s13, 2
	s_cbranch_scc0 .Lpb_done
	v_cvt_pk_bf16_f32 v50, v50, v51
	v_cvt_pk_bf16_f32 v51, v52, v53
	s_add_u32 s2, s18, 0x800000
	s_addc_u32 s3, s19, 0
	global_store_dwordx2 v2, v[50:51], s[2:3]
.Lpb_done:
	v_readlane_b32 s68, v251, 2
	v_readlane_b32 s69, v251, 3
	s_cmpk_gt_i32 s10, 0x21ff
	s_cbranch_scc1 .LBB0_42
	s_load_dwordx2 s[2:3], s[16:17], 0x40
	s_load_dwordx2 s[4:5], s[16:17], 0x138
	v_mov_b32_e32 v3, 0
	v_or_b32_e32 v4, 0x100, v6
	v_lshlrev_b32_e32 v2, 4, v6
	v_or_b32_e32 v20, 0x140, v6
	s_waitcnt lgkmcnt(0)
	v_lshl_add_u64 v[10:11], s[2:3], 0, v[2:3]
	v_lshlrev_b32_e32 v2, 4, v4
	v_or_b32_e32 v22, 0x180, v6
	v_lshl_add_u64 v[12:13], s[2:3], 0, v[2:3]
	v_lshlrev_b32_e32 v2, 4, v20
	v_or_b32_e32 v24, 0x1c0, v6
	v_lshl_add_u64 v[14:15], s[2:3], 0, v[2:3]
	v_lshlrev_b32_e32 v2, 4, v22
	v_lshl_add_u64 v[16:17], s[2:3], 0, v[2:3]
	v_lshlrev_b32_e32 v2, 4, v24
	s_ashr_i32 s11, s10, 31
	v_lshl_add_u64 v[18:19], s[2:3], 0, v[2:3]
	s_lshl_b64 s[2:3], s[10:11], 12
	s_add_u32 s2, s4, s2
	v_mov_b32_e32 v9, v3
	s_addc_u32 s3, s5, s3
	v_lshl_add_u64 v[2:3], s[2:3], 0, v[8:9]
	s_mov_b64 s[2:3], 0xd880000
	s_ashr_i32 s13, s12, 31
	v_lshl_add_u64 v[8:9], v[2:3], 0, s[2:3]
	s_lshl_b64 s[4:5], s[12:13], 12
	v_lshlrev_b32_e32 v1, 4, v6
	v_lshlrev_b32_e32 v6, 4, v4
	v_lshlrev_b32_e32 v7, 4, v20
	v_lshlrev_b32_e32 v20, 4, v22
	v_lshlrev_b32_e32 v21, 4, v24
	v_mov_b32_e32 v22, 0x358637bd
	s_mov_b32 s2, 0x800000
